# G3: gate loads (8/unit) issued right after the LDS-stage barrier, before the MFMA section (were in the tail after the 3rd barrier)
# speedup vs baseline: 1.0063x; 1.0033x over previous
; __device__ __forceinline__ unsigned pk2(float lo, float hi) { return pg8::pkc(lo, hi); }
; #define GLA_BAR() do { asm volatile("s_waitcnt lgkmcnt(0)" ::: "memory"); __builtin_amdgcn_s_barrier(); asm volatile("" ::: "memory"); } while (0)
; __device__ __forceinline__ void ph_g3(Frame& F, int e, int nrc) {
;     ...
;         GLA_BAR();
;         const int t = 32 * tb + r32;
;         const float tot = (SS[t] + SS[64 + t]) + (SS[128 + t] + SS[192 + t]);
;         const float rn = __builtin_amdgcn_rsqf(tot * (1.0f / 128.0f) + EPS);
;         const size_t row = (size_t)rc * 64 + t;
; #pragma unroll
;         for (int g4 = 0; g4 < 4; ++g4) { const int dv0 = 32 * db + 8 * g4 + 4 * hi;
;             const v2u gw = *(const v2u*)(P + row * DINP + C_GB + 128 * h + dv0); const f32x4 gn = *(const f32x4*)(gg + 128 * h + dv0);
;             const float g0 = bflo(gw.x), g1 = bfhi(gw.x), g2 = bflo(gw.y), g3 = bfhi(gw.y);
;             const float y0 = o[4 * g4 + 0] * rn * gn.x * (g0 * __builtin_amdgcn_rcpf(1.0f + __expf(-g0))), y1 = o[4 * g4 + 1] * rn * gn.y * (g1 * __builtin_amdgcn_rcpf(1.0f + __expf(-g1)));
;             const float y2 = o[4 * g4 + 2] * rn * gn.z * (g2 * __builtin_amdgcn_rcpf(1.0f + __expf(-g2))), y3 = o[4 * g4 + 3] * rn * gn.w * (g3 * __builtin_amdgcn_rcpf(1.0f + __expf(-g3)));
;             v2u w; w.x = pk2(y0, y1); w.y = pk2(y2, y3);
;             *(v2u*)(MIX + row * D + 1024 + 128 * h + dv0) = w; }
.LBB0_996:
	s_or_b64 exec, exec, s[18:19]
	s_waitcnt lgkmcnt(0)
	s_barrier
	ds_read2st64_b32 v[20:21], v151 offset0:216 offset1:217
	ds_read2st64_b32 v[22:23], v151 offset0:218 offset1:219
	s_ashr_i32 s18, s9, 3
	s_ashr_i32 s19, s18, 31
	s_lshl_b64 s[18:19], s[18:19], 6
	s_waitcnt lgkmcnt(1)
	v_mov_b32_e32 v24, v20
	s_waitcnt lgkmcnt(0)
	v_mov_b32_e32 v25, v22
	v_mov_b32_e32 v22, v21
	v_pk_add_f32 v[20:21], v[24:25], v[22:23]
	v_or_b32_e32 v22, s18, v142
	v_mov_b64_e32 v[24:25], s[12:13]
	s_movk_i32 s9, 0x3200
	v_add_f32_e32 v20, v20, v21
	v_mov_b32_e32 v23, s19
	v_mad_u64_u32 v[24:25], vcc, v22, s9, v[24:25]
	v_mov_b32_e32 v21, 0x3200
	s_and_b32 s9, s21, 0x380
	v_mad_i32_i24 v25, s19, v21, v25
	s_lshl_b32 s30, s9, 1
	v_lshlrev_b64 v[22:23], 12, v[22:23]
	v_lshl_add_u64 v[24:25], v[24:25], 0, s[30:31]
	v_lshl_add_u64 v[22:23], s[22:23], 0, v[22:23]
	v_lshl_add_u64 v[30:31], v[22:23], 0, s[30:31]
	v_lshl_add_u64 v[22:23], v[24:25], 0, v[146:147]
	s_mov_b64 s[18:19], 0x2800
	v_lshl_add_u64 v[24:25], v[22:23], 0, s[18:19]
	v_add_co_u32_e32 v22, vcc, s3, v22
	s_lshl_b32 s30, s9, 2
	s_nop 0
	v_addc_co_u32_e32 v23, vcc, 0, v23, vcc
	v_lshl_add_u64 v[22:23], v[144:145], 0, s[30:31]
	v_fmamk_f32 v20, v20, 0x3c000000, v244
	v_rsq_f32_e32 v20, v20
	s_mov_b64 s[18:19], 0x21e00800
	s_mov_b32 s9, 0x21e00000
	s_waitcnt vmcnt(5)
	v_mov_b64_e32 v[44:45], v[84:85]
	v_mov_b64_e32 v[40:41], v[88:89]
	v_mov_b64_e32 v[46:47], v[86:87]
	v_mov_b64_e32 v[42:43], v[90:91]
	s_waitcnt vmcnt(0)
	v_lshlrev_b32_e32 v34, 16, v188
	v_mul_f32_e32 v21, 0xbfb8aa3b, v34
	v_exp_f32_e32 v21, v21
	v_and_b32_e32 v35, 0xffff0000, v188
	v_add_f32_e32 v21, 1.0, v21
	v_rcp_f32_e32 v36, v21
	v_pk_mul_f32 v[4:5], v[4:5], v[20:21] op_sel_hi:[1,0]
	v_mul_f32_e32 v21, 0xbfb8aa3b, v35
	v_exp_f32_e32 v21, v21
	v_pk_mul_f32 v[4:5], v[190:191], v[4:5]
	v_add_f32_e32 v21, 1.0, v21
	v_rcp_f32_e32 v37, v21
	s_nop 0
	v_pk_mul_f32 v[26:27], v[36:37], v[34:35]
	s_nop 0
	v_pk_mul_f32 v[4:5], v[4:5], v[26:27]
	v_lshlrev_b32_e32 v26, 16, v189
	v_mul_f32_e32 v21, 0xbfb8aa3b, v26
	v_exp_f32_e32 v21, v21
	v_and_b32_e32 v27, 0xffff0000, v189
	v_mov_b64_e32 v[36:37], v[92:93]
	v_mov_b64_e32 v[38:39], v[94:95]
	v_add_f32_e32 v21, 1.0, v21
	v_rcp_f32_e32 v32, v21
	v_pk_mul_f32 v[6:7], v[6:7], v[20:21] op_sel_hi:[1,0]
	v_mul_f32_e32 v21, 0xbfb8aa3b, v27
	v_exp_f32_e32 v21, v21
	v_pk_mul_f32 v[6:7], v[192:193], v[6:7]
	v_add_f32_e32 v21, 1.0, v21
	v_rcp_f32_e32 v33, v21
	v_pk_mul_f32 v[8:9], v[8:9], v[20:21] op_sel_hi:[1,0]
	v_pk_mul_f32 v[26:27], v[32:33], v[26:27]
	s_nop 0
	v_pk_mul_f32 v[6:7], v[6:7], v[26:27]
	v_cvt_pk_bf16_f32 v26, v4, v5
	v_cvt_pk_bf16_f32 v27, v6, v7
	v_lshl_add_u64 v[6:7], v[30:31], 0, v[146:147]
	v_lshl_add_u64 v[4:5], v[6:7], 0, s[18:19]
	v_add_co_u32_e32 v6, vcc, s9, v6
	v_readlane_b32 s9, v254, 63
	s_nop 0
	v_addc_co_u32_e32 v7, vcc, 0, v7, vcc
	global_store_dwordx2 v[6:7], v[26:27], off offset:2048
	s_add_i32 s21, s21, s9
	s_andn2_b64 vcc, exec, s[10:11]
	s_mov_b32 s9, s8
	v_lshlrev_b32_e32 v30, 16, v194
	v_and_b32_e32 v31, 0xffff0000, v194
	v_mul_f32_e32 v6, 0xbfb8aa3b, v30
	v_exp_f32_e32 v6, v6
	v_pk_mul_f32 v[8:9], v[8:9], v[196:197]
	v_add_f32_e32 v6, 1.0, v6
	v_rcp_f32_e32 v32, v6
	v_mul_f32_e32 v6, 0xbfb8aa3b, v31
	v_exp_f32_e32 v6, v6
	s_nop 0
	v_add_f32_e32 v6, 1.0, v6
	v_rcp_f32_e32 v33, v6
	v_lshlrev_b32_e32 v6, 16, v195
	v_mul_f32_e32 v21, 0xbfb8aa3b, v6
	v_exp_f32_e32 v21, v21
	v_pk_mul_f32 v[26:27], v[32:33], v[30:31]
	v_and_b32_e32 v7, 0xffff0000, v195
	v_pk_mul_f32 v[8:9], v[8:9], v[26:27]
	v_add_f32_e32 v21, 1.0, v21
	v_rcp_f32_e32 v26, v21
	v_pk_mul_f32 v[10:11], v[10:11], v[20:21] op_sel_hi:[1,0]
	v_mul_f32_e32 v21, 0xbfb8aa3b, v7
	v_exp_f32_e32 v21, v21
	v_pk_mul_f32 v[10:11], v[10:11], v[198:199]
	v_cvt_pk_bf16_f32 v8, v8, v9
	v_add_f32_e32 v21, 1.0, v21
	v_rcp_f32_e32 v27, v21
	v_pk_mul_f32 v[12:13], v[12:13], v[20:21] op_sel_hi:[1,0]
	v_pk_mul_f32 v[14:15], v[14:15], v[20:21] op_sel_hi:[1,0]
	v_pk_mul_f32 v[16:17], v[16:17], v[20:21] op_sel_hi:[1,0]
	v_pk_mul_f32 v[6:7], v[26:27], v[6:7]
	s_nop 0
	v_pk_mul_f32 v[6:7], v[10:11], v[6:7]
	s_nop 0
	v_cvt_pk_bf16_f32 v9, v6, v7
	global_store_dwordx2 v[4:5], v[8:9], off offset:16
	v_lshlrev_b32_e32 v26, 16, v200
	v_and_b32_e32 v27, 0xffff0000, v200
	v_mul_f32_e32 v10, 0xbfb8aa3b, v26
	v_exp_f32_e32 v10, v10
	v_pk_mul_f32 v[6:7], v[12:13], v[202:203]
	v_pk_mul_f32 v[8:9], v[14:15], v[204:205]
	v_add_f32_e32 v10, 1.0, v10
	v_rcp_f32_e32 v28, v10
	v_mul_f32_e32 v10, 0xbfb8aa3b, v27
	v_exp_f32_e32 v10, v10
	s_nop 0
	v_add_f32_e32 v10, 1.0, v10
	v_rcp_f32_e32 v29, v10
	v_lshlrev_b32_e32 v10, 16, v201
	v_and_b32_e32 v11, 0xffff0000, v201
	v_pk_mul_f32 v[12:13], v[28:29], v[26:27]
	s_nop 0
	v_pk_mul_f32 v[6:7], v[6:7], v[12:13]
	v_mul_f32_e32 v12, 0xbfb8aa3b, v10
	v_mul_f32_e32 v13, 0xbfb8aa3b, v11
	v_exp_f32_e32 v12, v12
	v_exp_f32_e32 v13, v13
	v_cvt_pk_bf16_f32 v6, v6, v7
	v_add_f32_e32 v12, 1.0, v12
	v_add_f32_e32 v13, 1.0, v13
	v_rcp_f32_e32 v12, v12
	v_rcp_f32_e32 v13, v13
	s_nop 0
	v_pk_mul_f32 v[10:11], v[12:13], v[10:11]
	s_nop 0
	v_pk_mul_f32 v[8:9], v[8:9], v[10:11]
	s_nop 0
	v_cvt_pk_bf16_f32 v7, v8, v9
	global_store_dwordx2 v[4:5], v[6:7], off offset:32
	v_lshlrev_b32_e32 v12, 16, v206
	v_and_b32_e32 v13, 0xffff0000, v206
	v_mul_f32_e32 v6, 0xbfb8aa3b, v12
	v_exp_f32_e32 v6, v6
	v_pk_mul_f32 v[8:9], v[16:17], v[208:209]
	v_add_f32_e32 v6, 1.0, v6
	v_rcp_f32_e32 v14, v6
	v_mul_f32_e32 v6, 0xbfb8aa3b, v13
	v_exp_f32_e32 v6, v6
	s_nop 0
	v_add_f32_e32 v6, 1.0, v6
	v_rcp_f32_e32 v15, v6
	v_lshlrev_b32_e32 v6, 16, v207
	v_and_b32_e32 v7, 0xffff0000, v207
	v_pk_mul_f32 v[12:13], v[14:15], v[12:13]
	s_nop 0
	v_pk_mul_f32 v[8:9], v[8:9], v[12:13]
	v_mul_f32_e32 v12, 0xbfb8aa3b, v6
	v_mul_f32_e32 v13, 0xbfb8aa3b, v7
	v_exp_f32_e32 v12, v12
	v_exp_f32_e32 v13, v13
	v_pk_mul_f32 v[14:15], v[18:19], v[20:21] op_sel_hi:[1,0]
	v_cvt_pk_bf16_f32 v8, v8, v9
	v_add_f32_e32 v12, 1.0, v12
	v_add_f32_e32 v13, 1.0, v13
	v_rcp_f32_e32 v12, v12
	v_rcp_f32_e32 v13, v13
	v_pk_mul_f32 v[10:11], v[14:15], v[210:211]
	v_mov_b64_e32 v[16:17], v[80:81]
	v_mov_b64_e32 v[20:21], v[76:77]
	v_pk_mul_f32 v[6:7], v[12:13], v[6:7]
	v_mov_b64_e32 v[12:13], v[100:101]
	v_pk_mul_f32 v[6:7], v[10:11], v[6:7]
	v_mov_b64_e32 v[18:19], v[82:83]
	v_cvt_pk_bf16_f32 v9, v6, v7
	global_store_dwordx2 v[4:5], v[8:9], off offset:48
	v_mov_b64_e32 v[4:5], v[96:97]
	v_mov_b64_e32 v[8:9], v[104:105]
	v_mov_b64_e32 v[6:7], v[98:99]
	v_mov_b64_e32 v[22:23], v[78:79]
	v_mov_b64_e32 v[14:15], v[102:103]
	v_mov_b64_e32 v[10:11], v[106:107]
	s_cbranch_vccz .LBB0_1005
; #define LAS __attribute__((address_space(3)))
; #define GLA_BAR() do { asm volatile("s_waitcnt lgkmcnt(0)" ::: "memory"); __builtin_amdgcn_s_barrier(); asm volatile("" ::: "memory"); } while (0)
; __device__ __forceinline__ void ph_g3(Frame& F, int e, int nrc) {
;     ...
;         GLA_BAR();
;         { LAS unsigned* dst = (LAS unsigned*)(VT + s_d8 * PITCH + s_tp);
;             dst[0 * (PITCH / 2)] = (pv0.x & 0xffffu) | (pv1.x << 16); dst[1 * (PITCH / 2)] = (pv0.x >> 16) | (pv1.x & 0xffff0000u);
;             dst[2 * (PITCH / 2)] = (pv0.y & 0xffffu) | (pv1.y << 16); dst[3 * (PITCH / 2)] = (pv0.y >> 16) | (pv1.y & 0xffff0000u);
;             dst[4 * (PITCH / 2)] = (pv0.z & 0xffffu) | (pv1.z << 16); dst[5 * (PITCH / 2)] = (pv0.z >> 16) | (pv1.z & 0xffff0000u);
;             dst[6 * (PITCH / 2)] = (pv0.w & 0xffffu) | (pv1.w << 16); dst[7 * (PITCH / 2)] = (pv0.w >> 16) | (pv1.w & 0xffff0000u);
;             const int lo = s_t * PITCH + s_c8;
;             *(LAS v4u*)(QFl + lo) = pqf; *(LAS v4u*)(KFl + lo) = pkf; *(LAS v4u*)(QBl + lo) = pqb; *(LAS v4u*)(KBl + lo) = pkb; }
;         bf16x8 sf[4], sb[4];
; #pragma unroll
;         for (int ks = 0; ks < 4; ++ks) { sf[ks] = nsf[ks]; sb[ks] = nsb[ks]; }
;         GLA_BAR();
;         if (u + F.G < nrc * 8) G3_LOAD(u + F.G);
;     ...
;             const v2u gw = *(const v2u*)(P + row * DINP + C_GB + 128 * h + dv0); const f32x4 gn = *(const f32x4*)(gg + 128 * h + dv0);
.LBB0_997:
	v_and_b32_e32 v24, 0xffff, v52
	v_lshrrev_b32_e32 v25, 16, v52
	s_mov_b32 s8, 0xffff0000
	v_lshl_or_b32 v24, v56, 16, v24
	v_and_or_b32 v25, v56, s8, v25
	s_waitcnt lgkmcnt(0)
	s_barrier
	ds_write2_b32 v153, v24, v25 offset1:36
	v_and_b32_e32 v24, 0xffff, v53
	v_lshrrev_b32_e32 v25, 16, v53
	v_lshl_or_b32 v24, v57, 16, v24
	v_and_or_b32 v25, v57, s8, v25
	ds_write2_b32 v153, v24, v25 offset0:72 offset1:108
	v_and_b32_e32 v24, 0xffff, v54
	v_lshrrev_b32_e32 v25, 16, v54
	v_lshl_or_b32 v24, v58, 16, v24
	v_and_or_b32 v25, v58, s8, v25
	ds_write2_b32 v153, v24, v25 offset0:144 offset1:180
	v_and_b32_e32 v24, 0xffff, v55
	v_lshrrev_b32_e32 v25, 16, v55
	v_lshl_or_b32 v24, v59, 16, v24
	v_and_or_b32 v25, v59, s8, v25
	v_readlane_b32 s8, v253, 4
	ds_write2_b32 v153, v24, v25 offset0:216 offset1:252
	ds_write_b128 v143, v[60:63] offset:18432
	ds_write_b128 v143, v[64:67] offset:27648
	ds_write_b128 v143, v[68:71] offset:36864
	ds_write_b128 v143, v[72:75] offset:46080
	s_add_i32 s8, s9, s8
	s_waitcnt lgkmcnt(0)
	s_barrier
	s_ashr_i32 s32, s9, 3
	s_lshl_b32 s32, s32, 6
	v_or_b32_e32 v180, s32, v142
	v_mov_b64_e32 v[182:183], s[12:13]
	s_movk_i32 s99, 0x3200
	v_mad_u64_u32 v[182:183], vcc, v180, s99, v[182:183]
	s_and_b32 s32, s21, 0x380
	s_lshl_b32 s99, s32, 1
	s_addk_i32 s99, 0x2800
	s_lshl_b32 s32, s32, 2
	v_add_co_u32_e32 v182, vcc, s99, v182
	s_nop 1
	v_addc_co_u32_e32 v183, vcc, 0, v183, vcc
	v_lshl_add_u64 v[182:183], v[182:183], 0, v[146:147]
	v_add_co_u32_e32 v186, vcc, s32, v144
	s_nop 1
	v_addc_co_u32_e32 v187, vcc, 0, v145, vcc
	global_load_dwordx2 v[188:189], v[182:183], off
	global_load_dwordx4 v[190:193], v[186:187], off
	global_load_dwordx2 v[194:195], v[182:183], off offset:16
	global_load_dwordx4 v[196:199], v[186:187], off offset:32
	global_load_dwordx2 v[200:201], v[182:183], off offset:32
	global_load_dwordx4 v[202:205], v[186:187], off offset:64
	global_load_dwordx2 v[206:207], v[182:183], off offset:48
	global_load_dwordx4 v[208:211], v[186:187], off offset:96
	s_cmp_ge_i32 s8, s20
	s_cselect_b64 s[10:11], -1, 0
	s_and_b64 vcc, exec, s[10:11]
	s_cbranch_vccnz .LBB0_999
	s_ashr_i32 s18, s8, 3
	s_and_b32 s19, s18, 63
	s_and_b32 s30, s18, 3
	s_sub_i32 vcc_lo, 0x43, s19
	s_xor_b32 vcc_hi, s30, 3
	s_cmpk_lt_i32 s18, 0x100
	s_cselect_b32 s27, vcc_lo, vcc_hi
	s_add_i32 s19, s19, 4
	s_cmpk_lt_i32 s18, 0x100
	s_cselect_b32 s30, s19, s30
	s_add_i32 vcc_lo, s18, 0x3fffff00
	s_ashr_i32 s19, s8, 9
	s_lshr_b32 vcc_lo, vcc_lo, 2
	s_cmpk_lt_i32 s18, 0x100
	s_cselect_b32 s28, s19, vcc_lo
	s_and_b32 s17, s8, 7
	s_ashr_i32 s19, s18, 31
	s_mul_i32 vcc_hi, s18, 0xc8000
	s_mul_hi_i32 vcc_lo, s18, 0xc8000
	s_add_u32 vcc_hi, s12, vcc_hi
	s_addc_u32 s15, s13, vcc_lo
	s_lshl_b32 s16, s17, 7
	s_lshl_b32 vcc_lo, s17, 8
	s_add_u32 vcc_lo, vcc_hi, vcc_lo
	s_addc_u32 vcc_hi, s15, 0
	v_lshl_add_u64 v[24:25], v[2:3], 1, vcc
	v_add_co_u32_e32 v26, vcc, s3, v24
	s_movk_i32 s2, 0x5000
	s_nop 0
	v_addc_co_u32_e32 v27, vcc, 0, v25, vcc
	s_lshl_b64 s[18:19], s[18:19], 16
	v_add_co_u32_e32 v24, vcc, s2, v24
	s_or_b32 s18, s18, s16
	s_lshl_b32 s15, s28, 4
	s_lshl_b32 s16, s17, 1
	v_addc_co_u32_e32 v25, vcc, 0, v25, vcc
	s_or_b32 s15, s15, s16
	global_load_dwordx4 v[52:55], v[26:27], off
	global_load_dwordx4 v[56:59], v[24:25], off offset:512
	v_lshl_add_u64 v[24:25], v[132:133], 0, s[18:19]
	v_lshl_add_u64 v[26:27], v[134:135], 0, s[18:19]
	s_mul_i32 s17, s15, 0x44
	global_load_dwordx4 v[60:63], v[24:25], off
	global_load_dwordx4 v[64:67], v[26:27], off
	v_lshl_add_u64 v[24:25], v[136:137], 0, s[18:19]
	v_lshl_add_u64 v[26:27], v[138:139], 0, s[18:19]
	s_mul_hi_i32 s16, s15, 0x44
	s_add_u32 s18, s17, s30
	s_addc_u32 s19, s16, 0
	s_or_b32 s15, s15, 1
	s_lshl_b64 s[18:19], s[18:19], 14
	s_mul_hi_i32 s16, s15, 0x44
	s_mulk_i32 s15, 0x44
	s_add_u32 vcc_lo, s15, s27
	s_addc_u32 vcc_hi, s16, 0
	global_load_dwordx4 v[68:71], v[24:25], off
	global_load_dwordx4 v[72:75], v[26:27], off
	s_lshl_b64 vcc, vcc, 14
	v_lshl_add_u64 v[24:25], v[140:141], 0, s[18:19]
	v_lshl_add_u64 v[26:27], v[140:141], 0, vcc
	global_load_dwordx4 v[76:79], v[24:25], off
	global_load_dwordx4 v[88:91], v[24:25], off offset:32
	global_load_dwordx4 v[84:87], v[26:27], off
	global_load_dwordx4 v[80:83], v[26:27], off offset:32
	global_load_dwordx4 v[100:103], v[24:25], off offset:64
	global_load_dwordx4 v[104:107], v[24:25], off offset:96
	global_load_dwordx4 v[96:99], v[26:27], off offset:64
	global_load_dwordx4 v[92:95], v[26:27], off offset:96
	v_readlane_b32 s28, v255, 17
	v_readlane_b32 s27, v255, 16
	v_readlane_b32 s2, v253, 9
	v_readlane_b32 s16, v255, 14
	v_readlane_b32 s17, v255, 15
